# MLA-up GEMM epilogue: adjacent 8-byte store pairs merged into 16-byte stores after a 16-lane swap (half the store instructions)
# speedup vs baseline: 1.0122x; 1.0009x over previous
; __device__ __forceinline__ int ltid(int wv) { unsigned z = 0u; asm volatile("" : "+v"(z)); return wv * 64 + (int)__builtin_amdgcn_mbcnt_hi(~0u, __builtin_amdgcn_mbcnt_lo(~0u, z)); }
; #define EPI_LOOP_ROWS for (int ai = 0; ai < 2; ++ai) _Pragma("unroll") for (int m = 0; m < 4; ++m)
;     __device__ __forceinline__ void operator()(const f32x4 (&acc)[2][2][4][2], const Unit& u, int wv) const {
;         const int t_ = ltid(wv), wid_ = __builtin_amdgcn_readfirstlane(t_ >> 6), wr = wid_ >> 2, wc = wid_ & 3, fr = t_ & 15, fq = (t_ & 63) >> 4;
;         const int row0 = u.pm * BM + wr * 64 + fr;
;         float rq[2][4], rkv[2][4];
; #pragma unroll
;         EPI_LOOP_ROWS { const f32x4* p_ = (const f32x4*)(RSM + (size_t)(row0 + ai * HALF + m * 16) * 8); const f32x4 a_ = p_[0], b_ = p_[1];
;             rq[ai][m] = rsqrtf(((a_.x + a_.y) + (a_.z + a_.w)) * (1.0f / 256.0f) + EPS); rkv[ai][m] = rsqrtf(((b_.x + b_.y) + (b_.z + b_.w)) * (1.0f / 128.0f) + EPS); }
; #pragma unroll
;         for (int bj = 0; bj < 2; ++bj) {
;             const int cg = u.pn * BM + bj * HALF + wc * 32;
;             const bool rope = (cg < 768) && ((cg % 96) == 64);
;             const int kind = (cg < 384) ? 0 : ((cg < 768 && rope) ? 2 : 1);
.LBB0_559:
	v_mbcnt_lo_u32_b32 v244, -1, 0
	v_mbcnt_hi_u32_b32 v244, -1, v244
	v_bfe_u32 v244, v244, 4, 1
	v_mul_u32_u24_e32 v244, 24, v244
	v_mov_b32_e32 v245, 0
	v_mov_b32_e32 v0, v1
	s_lshl_b32 s1, s6, 8
	v_mbcnt_lo_u32_b32 v0, -1, v0
	v_mbcnt_hi_u32_b32 v0, -1, v0
	v_add_u32_e32 v114, s27, v0
	s_mov_b64 s[6:7], 0
	v_readfirstlane_b32 s0, v114
	s_ashr_i32 s5, s0, 2
	s_andn2_b32 s5, s5, 63
	s_add_i32 s5, s5, s1
	v_and_or_b32 v222, v0, 15, s5
	v_ashrrev_i32_e32 v223, 31, v222
	v_lshlrev_b64 v[114:115], 5, v[222:223]
	v_or_b32_e32 v220, 16, v222
	v_lshl_add_u64 v[114:115], s[66:67], 0, v[114:115]
	v_ashrrev_i32_e32 v221, 31, v220
	global_load_dwordx4 v[186:189], v[114:115], off offset:16
	global_load_dwordx4 v[190:193], v[114:115], off
	v_lshlrev_b64 v[114:115], 5, v[220:221]
	v_or_b32_e32 v218, 32, v222
	v_lshl_add_u64 v[114:115], s[66:67], 0, v[114:115]
	v_ashrrev_i32_e32 v219, 31, v218
	global_load_dwordx4 v[178:181], v[114:115], off offset:16
	global_load_dwordx4 v[182:185], v[114:115], off
	v_lshlrev_b64 v[114:115], 5, v[218:219]
	v_or_b32_e32 v216, 48, v222
	v_lshl_add_u64 v[114:115], s[66:67], 0, v[114:115]
	v_ashrrev_i32_e32 v217, 31, v216
	global_load_dwordx4 v[170:173], v[114:115], off offset:16
	global_load_dwordx4 v[174:177], v[114:115], off
	v_lshlrev_b64 v[114:115], 5, v[216:217]
	v_add_u32_e32 v214, 0x80, v222
	v_lshl_add_u64 v[114:115], s[66:67], 0, v[114:115]
	v_ashrrev_i32_e32 v215, 31, v214
	global_load_dwordx4 v[162:165], v[114:115], off offset:16
	global_load_dwordx4 v[166:169], v[114:115], off
	v_lshlrev_b64 v[114:115], 5, v[214:215]
	v_add_u32_e32 v212, 0x90, v222
	v_lshl_add_u64 v[114:115], s[66:67], 0, v[114:115]
	v_ashrrev_i32_e32 v213, 31, v212
	global_load_dwordx4 v[154:157], v[114:115], off offset:16
	global_load_dwordx4 v[158:161], v[114:115], off
	v_lshlrev_b64 v[114:115], 5, v[212:213]
	v_add_u32_e32 v210, 0xa0, v222
	v_lshl_add_u64 v[114:115], s[66:67], 0, v[114:115]
	v_ashrrev_i32_e32 v211, 31, v210
	global_load_dwordx4 v[146:149], v[114:115], off offset:16
	global_load_dwordx4 v[150:153], v[114:115], off
	v_lshlrev_b64 v[114:115], 5, v[210:211]
	v_add_u32_e32 v208, 0xb0, v222
	v_lshl_add_u64 v[114:115], s[66:67], 0, v[114:115]
	v_ashrrev_i32_e32 v209, 31, v208
	global_load_dwordx4 v[130:133], v[114:115], off offset:16
	global_load_dwordx4 v[134:137], v[114:115], off
	v_lshlrev_b64 v[114:115], 5, v[208:209]
	v_lshl_add_u64 v[118:119], s[66:67], 0, v[114:115]
	global_load_dwordx4 v[114:117], v[118:119], off offset:16
	s_nop 0
	global_load_dwordx4 v[118:121], v[118:119], off
	s_lshr_b32 s0, s0, 1
	s_lshl_b32 s1, s4, 8
	s_and_b32 s0, s0, 0x60
	s_or_b32 s78, s0, s1
	s_cmpk_lt_i32 s78, 0x300
	s_cselect_b64 s[4:5], -1, 0
	s_cmpk_gt_i32 s78, 0x2ff
	s_cbranch_scc1 .LBB0_561
	s_mul_hi_i32 s0, s78, 0x2aaaaaab
	s_lshr_b32 s1, s0, 31
	s_lshr_b32 s0, s0, 4
	s_add_i32 s0, s0, s1
	s_mulk_i32 s0, 0x60
	s_sub_i32 s0, s78, s0
	s_cmp_eq_u32 s0, 64
	s_cselect_b64 s[6:7], -1, 0

; __device__ __forceinline__ unsigned cvtpk(float lo, float hi) { f32x2 v = {lo, hi}; bf16x2_t b = __builtin_convertvector(v, bf16x2_t); return __builtin_bit_cast(unsigned, b); }
; #define EPI_LOOP_ROWS for (int ai = 0; ai < 2; ++ai) _Pragma("unroll") for (int m = 0; m < 4; ++m)
;     __device__ __forceinline__ void operator()(const f32x4 (&acc)[2][2][4][2], const Unit& u, int wv) const {
;     ...
;         EPI_LOOP_ROWS { const f32x4* p_ = (const f32x4*)(RSM + (size_t)(row0 + ai * HALF + m * 16) * 8); const f32x4 a_ = p_[0], b_ = p_[1];
;             rq[ai][m] = rsqrtf(((a_.x + a_.y) + (a_.z + a_.w)) * (1.0f / 256.0f) + EPS); rkv[ai][m] = rsqrtf(((b_.x + b_.y) + (b_.z + b_.w)) * (1.0f / 128.0f) + EPS); }
; #pragma unroll
;         for (int bj = 0; bj < 2; ++bj) {
;             const int cg = u.pn * BM + bj * HALF + wc * 32;
;             const bool rope = (cg < 768) && ((cg % 96) == 64);
;             const int kind = (cg < 384) ? 0 : ((cg < 768 && rope) ? 2 : 1);
; #pragma unroll
;             EPI_LOOP_ROWS { const int row = row0 + ai * HALF + m * 16; f32x4 v0 = acc[ai][bj][m][0], v1 = acc[ai][bj][m][1];
;                 const float sc = kind == 0 ? qscale * rq[ai][m] : (kind == 1 ? rkv[ai][m] : 1.0f);
;                 if (rope) { const int pos = row & (SEQ - 1); const f32x4 c = *(const f32x4*)(rcos + pos * 16 + 4 * fq), s = *(const f32x4*)(rsin + pos * 16 + 4 * fq);
;                     const f32x4 a = v0 * c - v1 * s, b = v0 * s + v1 * c; v0 = a; v1 = b; }
;                 v0 = v0 * sc; v1 = v1 * sc;
;                 bf16_t* p = O + (size_t)row * 1024 + cg + 4 * fq;
;                 u32x2 w0, w1; w0.x = cvtpk(v0[0], v0[1]); w0.y = cvtpk(v0[2], v0[3]); w1.x = cvtpk(v1[0], v1[1]); w1.y = cvtpk(v1[2], v1[3]);
;                 *(u32x2*)p = w0; *(u32x2*)(p + 16) = w1; } }
.LBB0_569:
	s_nop 0
	v_pk_mul_f32 v[190:191], v[186:187], v[138:139] op_sel_hi:[0,1]
	v_lshlrev_b64 v[138:139], 11, v[222:223]
	s_ashr_i32 s79, s78, 31
	v_lshl_add_u64 v[138:139], s[12:13], 0, v[138:139]
	v_pk_mul_f32 v[144:145], v[186:187], v[144:145] op_sel_hi:[0,1]
	v_pk_mul_f32 v[142:143], v[186:187], v[142:143] op_sel_hi:[0,1]
	v_lshl_add_u64 v[138:139], s[78:79], 1, v[138:139]
	v_lshlrev_b32_e32 v0, 1, v187
	v_pk_mul_f32 v[140:141], v[186:187], v[140:141] op_sel_hi:[0,1]
	v_lshl_add_u64 v[138:139], v[138:139], 0, v[0:1]
	v_cvt_pk_bf16_f32 v142, v142, v143
	v_cvt_pk_bf16_f32 v143, v144, v145
	v_cvt_pk_bf16_f32 v144, v190, v191
	v_cvt_pk_bf16_f32 v145, v140, v141
	v_mov_b32_e32 v238, v142
	v_mov_b32_e32 v239, v143
	v_mov_b32_e32 v240, v144
	v_mov_b32_e32 v241, v145
	s_nop 1
	v_permlane16_swap_b32 v238, v240
	v_permlane16_swap_b32 v239, v241
	v_lshl_add_u64 v[242:243], v[138:139], 0, v[244:245]
	global_store_dwordx4 v[242:243], v[238:241], off
	s_nop 1
	v_mov_b32_e32 v140, v183
	v_mov_b32_e32 v141, v184
	v_mov_b32_e32 v183, v185
	v_mov_b32_e32 v142, v179
	v_mov_b32_e32 v143, v180
	v_mov_b32_e32 v179, v181
	v_pk_add_f32 v[140:141], v[140:141], v[182:183]
	v_pk_add_f32 v[142:143], v[142:143], v[178:179]
	v_mov_b32_e32 v145, v140
	v_mov_b32_e32 v144, v142
	v_mov_b32_e32 v140, v143
	v_pk_add_f32 v[140:141], v[144:145], v[140:141]
	s_cmp_lt_i32 s10, 1
	v_pk_fma_f32 v[140:141], v[140:141], s[0:1], v[194:195] op_sel_hi:[1,1,0]
	s_mov_b64 s[80:81], -1
	v_mul_f32_e32 v142, 0x4b800000, v140
	v_cmp_gt_f32_e32 vcc, s97, v140
	v_cmp_gt_f32_e64 s[6:7], s97, v141
	s_nop 0
	v_cndmask_b32_e32 v140, v140, v142, vcc
	v_rsq_f32_e32 v140, v140
	s_nop 0
	v_mul_f32_e32 v142, 0x45800000, v140
	v_cndmask_b32_e32 v142, v140, v142, vcc
	s_cbranch_scc1 .LBB0_573
	s_cmp_lg_u32 s10, 1
	v_mov_b32_e32 v140, 1.0
	s_cbranch_scc1 .LBB0_572
	v_mov_b32_e32 v140, v142

; __device__ __forceinline__ unsigned cvtpk(float lo, float hi) { f32x2 v = {lo, hi}; bf16x2_t b = __builtin_convertvector(v, bf16x2_t); return __builtin_bit_cast(unsigned, b); }
; #define EPI_LOOP_ROWS for (int ai = 0; ai < 2; ++ai) _Pragma("unroll") for (int m = 0; m < 4; ++m)
;     __device__ __forceinline__ void operator()(const f32x4 (&acc)[2][2][4][2], const Unit& u, int wv) const {
;     ...
;         EPI_LOOP_ROWS { const f32x4* p_ = (const f32x4*)(RSM + (size_t)(row0 + ai * HALF + m * 16) * 8); const f32x4 a_ = p_[0], b_ = p_[1];
;             rq[ai][m] = rsqrtf(((a_.x + a_.y) + (a_.z + a_.w)) * (1.0f / 256.0f) + EPS); rkv[ai][m] = rsqrtf(((b_.x + b_.y) + (b_.z + b_.w)) * (1.0f / 128.0f) + EPS); }
; #pragma unroll
;         for (int bj = 0; bj < 2; ++bj) {
;             const int cg = u.pn * BM + bj * HALF + wc * 32;
;             const bool rope = (cg < 768) && ((cg % 96) == 64);
;             const int kind = (cg < 384) ? 0 : ((cg < 768 && rope) ? 2 : 1);
; #pragma unroll
;             EPI_LOOP_ROWS { const int row = row0 + ai * HALF + m * 16; f32x4 v0 = acc[ai][bj][m][0], v1 = acc[ai][bj][m][1];
;                 const float sc = kind == 0 ? qscale * rq[ai][m] : (kind == 1 ? rkv[ai][m] : 1.0f);
;                 if (rope) { const int pos = row & (SEQ - 1); const f32x4 c = *(const f32x4*)(rcos + pos * 16 + 4 * fq), s = *(const f32x4*)(rsin + pos * 16 + 4 * fq);
;                     const f32x4 a = v0 * c - v1 * s, b = v0 * s + v1 * c; v0 = a; v1 = b; }
;                 v0 = v0 * sc; v1 = v1 * sc;
;                 bf16_t* p = O + (size_t)row * 1024 + cg + 4 * fq;
;                 u32x2 w0, w1; w0.x = cvtpk(v0[0], v0[1]); w0.y = cvtpk(v0[2], v0[3]); w1.x = cvtpk(v1[0], v1[1]); w1.y = cvtpk(v1[2], v1[3]);
;                 *(u32x2*)p = w0; *(u32x2*)(p + 16) = w1; } }
.LBB0_577:
	s_nop 0
	v_pk_mul_f32 v[144:145], v[140:141], v[122:123] op_sel_hi:[0,1]
	v_lshlrev_b64 v[122:123], 11, v[220:221]
	v_lshl_add_u64 v[122:123], s[12:13], 0, v[122:123]
	v_pk_mul_f32 v[128:129], v[140:141], v[128:129] op_sel_hi:[0,1]
	v_pk_mul_f32 v[126:127], v[140:141], v[126:127] op_sel_hi:[0,1]
	v_lshl_add_u64 v[122:123], s[78:79], 1, v[122:123]
	v_pk_mul_f32 v[124:125], v[140:141], v[124:125] op_sel_hi:[0,1]
	v_lshl_add_u64 v[122:123], v[122:123], 0, v[0:1]
	v_cvt_pk_bf16_f32 v126, v126, v127
	v_cvt_pk_bf16_f32 v127, v128, v129
	v_cvt_pk_bf16_f32 v128, v144, v145
	v_cvt_pk_bf16_f32 v129, v124, v125
	v_mov_b32_e32 v238, v126
	v_mov_b32_e32 v239, v127
	v_mov_b32_e32 v240, v128
	v_mov_b32_e32 v241, v129
	s_nop 1
	v_permlane16_swap_b32 v238, v240
	v_permlane16_swap_b32 v239, v241
	v_lshl_add_u64 v[242:243], v[122:123], 0, v[244:245]
	global_store_dwordx4 v[242:243], v[238:241], off
	s_nop 1
	v_mov_b32_e32 v124, v175
	v_mov_b32_e32 v125, v176
	v_mov_b32_e32 v175, v177
	v_mov_b32_e32 v126, v171
	v_mov_b32_e32 v127, v172
	v_mov_b32_e32 v171, v173
	v_pk_add_f32 v[124:125], v[124:125], v[174:175]
	v_pk_add_f32 v[126:127], v[126:127], v[170:171]
	v_mov_b32_e32 v129, v124
	v_mov_b32_e32 v128, v126
	v_mov_b32_e32 v124, v127
	v_pk_add_f32 v[124:125], v[128:129], v[124:125]
	s_cmp_lt_i32 s10, 1
	v_pk_fma_f32 v[124:125], v[124:125], s[0:1], v[194:195] op_sel_hi:[1,1,0]
	s_mov_b64 s[80:81], -1
	v_mul_f32_e32 v126, 0x4b800000, v124
	v_cmp_gt_f32_e32 vcc, s97, v124
	v_cmp_gt_f32_e64 s[6:7], s97, v125
	s_nop 0
	v_cndmask_b32_e32 v124, v124, v126, vcc
	v_rsq_f32_e32 v124, v124
	s_nop 0
	v_mul_f32_e32 v126, 0x45800000, v124
	v_cndmask_b32_e32 v126, v124, v126, vcc
	s_cbranch_scc1 .LBB0_581
	s_cmp_lg_u32 s10, 1
	v_mov_b32_e32 v124, 1.0
	s_cbranch_scc1 .LBB0_580
	v_mov_b32_e32 v124, v126

; __device__ __forceinline__ unsigned cvtpk(float lo, float hi) { f32x2 v = {lo, hi}; bf16x2_t b = __builtin_convertvector(v, bf16x2_t); return __builtin_bit_cast(unsigned, b); }
; #define EPI_LOOP_ROWS for (int ai = 0; ai < 2; ++ai) _Pragma("unroll") for (int m = 0; m < 4; ++m)
;     __device__ __forceinline__ void operator()(const f32x4 (&acc)[2][2][4][2], const Unit& u, int wv) const {
;     ...
;         EPI_LOOP_ROWS { const f32x4* p_ = (const f32x4*)(RSM + (size_t)(row0 + ai * HALF + m * 16) * 8); const f32x4 a_ = p_[0], b_ = p_[1];
;             rq[ai][m] = rsqrtf(((a_.x + a_.y) + (a_.z + a_.w)) * (1.0f / 256.0f) + EPS); rkv[ai][m] = rsqrtf(((b_.x + b_.y) + (b_.z + b_.w)) * (1.0f / 128.0f) + EPS); }
; #pragma unroll
;         for (int bj = 0; bj < 2; ++bj) {
;             const int cg = u.pn * BM + bj * HALF + wc * 32;
;             const bool rope = (cg < 768) && ((cg % 96) == 64);
;             const int kind = (cg < 384) ? 0 : ((cg < 768 && rope) ? 2 : 1);
; #pragma unroll
;             EPI_LOOP_ROWS { const int row = row0 + ai * HALF + m * 16; f32x4 v0 = acc[ai][bj][m][0], v1 = acc[ai][bj][m][1];
;                 const float sc = kind == 0 ? qscale * rq[ai][m] : (kind == 1 ? rkv[ai][m] : 1.0f);
;                 if (rope) { const int pos = row & (SEQ - 1); const f32x4 c = *(const f32x4*)(rcos + pos * 16 + 4 * fq), s = *(const f32x4*)(rsin + pos * 16 + 4 * fq);
;                     const f32x4 a = v0 * c - v1 * s, b = v0 * s + v1 * c; v0 = a; v1 = b; }
;                 v0 = v0 * sc; v1 = v1 * sc;
;                 bf16_t* p = O + (size_t)row * 1024 + cg + 4 * fq;
;                 u32x2 w0, w1; w0.x = cvtpk(v0[0], v0[1]); w0.y = cvtpk(v0[2], v0[3]); w1.x = cvtpk(v1[0], v1[1]); w1.y = cvtpk(v1[2], v1[3]);
;                 *(u32x2*)p = w0; *(u32x2*)(p + 16) = w1; } }
.LBB0_585:
	s_nop 0
	v_pk_mul_f32 v[128:129], v[124:125], v[106:107] op_sel_hi:[0,1]
	v_lshlrev_b64 v[106:107], 11, v[218:219]
	v_lshl_add_u64 v[106:107], s[12:13], 0, v[106:107]
	v_pk_mul_f32 v[112:113], v[124:125], v[112:113] op_sel_hi:[0,1]
	v_pk_mul_f32 v[110:111], v[124:125], v[110:111] op_sel_hi:[0,1]
	v_lshl_add_u64 v[106:107], s[78:79], 1, v[106:107]
	v_pk_mul_f32 v[108:109], v[124:125], v[108:109] op_sel_hi:[0,1]
	v_lshl_add_u64 v[106:107], v[106:107], 0, v[0:1]
	v_cvt_pk_bf16_f32 v110, v110, v111
	v_cvt_pk_bf16_f32 v111, v112, v113
	v_cvt_pk_bf16_f32 v112, v128, v129
	v_cvt_pk_bf16_f32 v113, v108, v109
	v_mov_b32_e32 v238, v110
	v_mov_b32_e32 v239, v111
	v_mov_b32_e32 v240, v112
	v_mov_b32_e32 v241, v113
	s_nop 1
	v_permlane16_swap_b32 v238, v240
	v_permlane16_swap_b32 v239, v241
	v_lshl_add_u64 v[242:243], v[106:107], 0, v[244:245]
	global_store_dwordx4 v[242:243], v[238:241], off
	s_nop 1
	v_mov_b32_e32 v108, v167
	v_mov_b32_e32 v109, v168
	v_mov_b32_e32 v167, v169
	v_mov_b32_e32 v110, v163
	v_mov_b32_e32 v111, v164
	v_mov_b32_e32 v163, v165
	v_pk_add_f32 v[108:109], v[108:109], v[166:167]
	v_pk_add_f32 v[110:111], v[110:111], v[162:163]
	v_mov_b32_e32 v113, v108
	v_mov_b32_e32 v112, v110
	v_mov_b32_e32 v108, v111
	v_pk_add_f32 v[108:109], v[112:113], v[108:109]
	s_cmp_lt_i32 s10, 1
	v_pk_fma_f32 v[108:109], v[108:109], s[0:1], v[194:195] op_sel_hi:[1,1,0]
	s_mov_b64 s[80:81], -1
	v_mul_f32_e32 v110, 0x4b800000, v108
	v_cmp_gt_f32_e32 vcc, s97, v108
	v_cmp_gt_f32_e64 s[6:7], s97, v109
	s_nop 0
	v_cndmask_b32_e32 v108, v108, v110, vcc
	v_rsq_f32_e32 v108, v108
	s_nop 0
	v_mul_f32_e32 v110, 0x45800000, v108
	v_cndmask_b32_e32 v110, v108, v110, vcc
	s_cbranch_scc1 .LBB0_589
	s_cmp_lg_u32 s10, 1
	v_mov_b32_e32 v108, 1.0
	s_cbranch_scc1 .LBB0_588
	v_mov_b32_e32 v108, v110

; __device__ __forceinline__ unsigned cvtpk(float lo, float hi) { f32x2 v = {lo, hi}; bf16x2_t b = __builtin_convertvector(v, bf16x2_t); return __builtin_bit_cast(unsigned, b); }
; #define EPI_LOOP_ROWS for (int ai = 0; ai < 2; ++ai) _Pragma("unroll") for (int m = 0; m < 4; ++m)
;     __device__ __forceinline__ void operator()(const f32x4 (&acc)[2][2][4][2], const Unit& u, int wv) const {
;     ...
;         EPI_LOOP_ROWS { const f32x4* p_ = (const f32x4*)(RSM + (size_t)(row0 + ai * HALF + m * 16) * 8); const f32x4 a_ = p_[0], b_ = p_[1];
;             rq[ai][m] = rsqrtf(((a_.x + a_.y) + (a_.z + a_.w)) * (1.0f / 256.0f) + EPS); rkv[ai][m] = rsqrtf(((b_.x + b_.y) + (b_.z + b_.w)) * (1.0f / 128.0f) + EPS); }
; #pragma unroll
;         for (int bj = 0; bj < 2; ++bj) {
;             const int cg = u.pn * BM + bj * HALF + wc * 32;
;             const bool rope = (cg < 768) && ((cg % 96) == 64);
;             const int kind = (cg < 384) ? 0 : ((cg < 768 && rope) ? 2 : 1);
; #pragma unroll
;             EPI_LOOP_ROWS { const int row = row0 + ai * HALF + m * 16; f32x4 v0 = acc[ai][bj][m][0], v1 = acc[ai][bj][m][1];
;                 const float sc = kind == 0 ? qscale * rq[ai][m] : (kind == 1 ? rkv[ai][m] : 1.0f);
;                 if (rope) { const int pos = row & (SEQ - 1); const f32x4 c = *(const f32x4*)(rcos + pos * 16 + 4 * fq), s = *(const f32x4*)(rsin + pos * 16 + 4 * fq);
;                     const f32x4 a = v0 * c - v1 * s, b = v0 * s + v1 * c; v0 = a; v1 = b; }
;                 v0 = v0 * sc; v1 = v1 * sc;
;                 bf16_t* p = O + (size_t)row * 1024 + cg + 4 * fq;
;                 u32x2 w0, w1; w0.x = cvtpk(v0[0], v0[1]); w0.y = cvtpk(v0[2], v0[3]); w1.x = cvtpk(v1[0], v1[1]); w1.y = cvtpk(v1[2], v1[3]);
;                 *(u32x2*)p = w0; *(u32x2*)(p + 16) = w1; } }
.LBB0_593:
	s_nop 0
	v_pk_mul_f32 v[112:113], v[108:109], v[98:99] op_sel_hi:[0,1]
	v_lshlrev_b64 v[98:99], 11, v[216:217]
	v_lshl_add_u64 v[98:99], s[12:13], 0, v[98:99]
	v_pk_mul_f32 v[104:105], v[108:109], v[104:105] op_sel_hi:[0,1]
	v_pk_mul_f32 v[102:103], v[108:109], v[102:103] op_sel_hi:[0,1]
	v_lshl_add_u64 v[98:99], s[78:79], 1, v[98:99]
	v_pk_mul_f32 v[100:101], v[108:109], v[100:101] op_sel_hi:[0,1]
	v_lshl_add_u64 v[98:99], v[98:99], 0, v[0:1]
	v_cvt_pk_bf16_f32 v102, v102, v103
	v_cvt_pk_bf16_f32 v103, v104, v105
	v_cvt_pk_bf16_f32 v104, v112, v113
	v_cvt_pk_bf16_f32 v105, v100, v101
	v_mov_b32_e32 v238, v102
	v_mov_b32_e32 v239, v103
	v_mov_b32_e32 v240, v104
	v_mov_b32_e32 v241, v105
	s_nop 1
	v_permlane16_swap_b32 v238, v240
	v_permlane16_swap_b32 v239, v241
	v_lshl_add_u64 v[242:243], v[98:99], 0, v[244:245]
	global_store_dwordx4 v[242:243], v[238:241], off
	s_nop 1
	v_mov_b32_e32 v100, v159
	v_mov_b32_e32 v101, v160
	v_mov_b32_e32 v159, v161
	v_mov_b32_e32 v102, v155
	v_mov_b32_e32 v103, v156
	v_mov_b32_e32 v155, v157
	v_pk_add_f32 v[100:101], v[100:101], v[158:159]
	v_pk_add_f32 v[102:103], v[102:103], v[154:155]
	v_mov_b32_e32 v105, v100
	v_mov_b32_e32 v104, v102
	v_mov_b32_e32 v100, v103
	v_pk_add_f32 v[100:101], v[104:105], v[100:101]
	s_cmp_lt_i32 s10, 1
	v_pk_fma_f32 v[100:101], v[100:101], s[0:1], v[194:195] op_sel_hi:[1,1,0]
	s_mov_b64 s[80:81], -1
	v_mul_f32_e32 v102, 0x4b800000, v100
	v_cmp_gt_f32_e32 vcc, s97, v100
	v_cmp_gt_f32_e64 s[6:7], s97, v101
	s_nop 0
	v_cndmask_b32_e32 v100, v100, v102, vcc
	v_rsq_f32_e32 v100, v100
	s_nop 0
	v_mul_f32_e32 v102, 0x45800000, v100
	v_cndmask_b32_e32 v102, v100, v102, vcc
	s_cbranch_scc1 .LBB0_597
	s_cmp_lg_u32 s10, 1
	v_mov_b32_e32 v100, 1.0
	s_cbranch_scc1 .LBB0_596
	v_mov_b32_e32 v100, v102

; __device__ __forceinline__ unsigned cvtpk(float lo, float hi) { f32x2 v = {lo, hi}; bf16x2_t b = __builtin_convertvector(v, bf16x2_t); return __builtin_bit_cast(unsigned, b); }
; #define EPI_LOOP_ROWS for (int ai = 0; ai < 2; ++ai) _Pragma("unroll") for (int m = 0; m < 4; ++m)
;     __device__ __forceinline__ void operator()(const f32x4 (&acc)[2][2][4][2], const Unit& u, int wv) const {
;     ...
;         EPI_LOOP_ROWS { const f32x4* p_ = (const f32x4*)(RSM + (size_t)(row0 + ai * HALF + m * 16) * 8); const f32x4 a_ = p_[0], b_ = p_[1];
;             rq[ai][m] = rsqrtf(((a_.x + a_.y) + (a_.z + a_.w)) * (1.0f / 256.0f) + EPS); rkv[ai][m] = rsqrtf(((b_.x + b_.y) + (b_.z + b_.w)) * (1.0f / 128.0f) + EPS); }
; #pragma unroll
;         for (int bj = 0; bj < 2; ++bj) {
;             const int cg = u.pn * BM + bj * HALF + wc * 32;
;             const bool rope = (cg < 768) && ((cg % 96) == 64);
;             const int kind = (cg < 384) ? 0 : ((cg < 768 && rope) ? 2 : 1);
; #pragma unroll
;             EPI_LOOP_ROWS { const int row = row0 + ai * HALF + m * 16; f32x4 v0 = acc[ai][bj][m][0], v1 = acc[ai][bj][m][1];
;                 const float sc = kind == 0 ? qscale * rq[ai][m] : (kind == 1 ? rkv[ai][m] : 1.0f);
;                 if (rope) { const int pos = row & (SEQ - 1); const f32x4 c = *(const f32x4*)(rcos + pos * 16 + 4 * fq), s = *(const f32x4*)(rsin + pos * 16 + 4 * fq);
;                     const f32x4 a = v0 * c - v1 * s, b = v0 * s + v1 * c; v0 = a; v1 = b; }
;                 v0 = v0 * sc; v1 = v1 * sc;
;                 bf16_t* p = O + (size_t)row * 1024 + cg + 4 * fq;
;                 u32x2 w0, w1; w0.x = cvtpk(v0[0], v0[1]); w0.y = cvtpk(v0[2], v0[3]); w1.x = cvtpk(v1[0], v1[1]); w1.y = cvtpk(v1[2], v1[3]);
;                 *(u32x2*)p = w0; *(u32x2*)(p + 16) = w1; } }
.LBB0_601:
	s_nop 0
	v_pk_mul_f32 v[104:105], v[100:101], v[90:91] op_sel_hi:[0,1]
	v_lshlrev_b64 v[90:91], 11, v[214:215]
	v_lshl_add_u64 v[90:91], s[12:13], 0, v[90:91]
	v_pk_mul_f32 v[96:97], v[100:101], v[96:97] op_sel_hi:[0,1]
	v_pk_mul_f32 v[94:95], v[100:101], v[94:95] op_sel_hi:[0,1]
	v_lshl_add_u64 v[90:91], s[78:79], 1, v[90:91]
	v_pk_mul_f32 v[92:93], v[100:101], v[92:93] op_sel_hi:[0,1]
	v_lshl_add_u64 v[90:91], v[90:91], 0, v[0:1]
	v_cvt_pk_bf16_f32 v94, v94, v95
	v_cvt_pk_bf16_f32 v95, v96, v97
	v_cvt_pk_bf16_f32 v96, v104, v105
	v_cvt_pk_bf16_f32 v97, v92, v93
	v_mov_b32_e32 v238, v94
	v_mov_b32_e32 v239, v95
	v_mov_b32_e32 v240, v96
	v_mov_b32_e32 v241, v97
	s_nop 1
	v_permlane16_swap_b32 v238, v240
	v_permlane16_swap_b32 v239, v241
	v_lshl_add_u64 v[242:243], v[90:91], 0, v[244:245]
	global_store_dwordx4 v[242:243], v[238:241], off
	s_nop 1
	v_mov_b32_e32 v92, v151
	v_mov_b32_e32 v93, v152
	v_mov_b32_e32 v151, v153
	v_mov_b32_e32 v94, v147
	v_mov_b32_e32 v95, v148
	v_mov_b32_e32 v147, v149
	v_pk_add_f32 v[92:93], v[92:93], v[150:151]
	v_pk_add_f32 v[94:95], v[94:95], v[146:147]
	v_mov_b32_e32 v97, v92
	v_mov_b32_e32 v96, v94
	v_mov_b32_e32 v92, v95
	v_pk_add_f32 v[92:93], v[96:97], v[92:93]
	s_cmp_lt_i32 s10, 1
	v_pk_fma_f32 v[92:93], v[92:93], s[0:1], v[194:195] op_sel_hi:[1,1,0]
	s_mov_b64 s[80:81], -1
	v_mul_f32_e32 v94, 0x4b800000, v92
	v_cmp_gt_f32_e32 vcc, s97, v92
	v_cmp_gt_f32_e64 s[6:7], s97, v93
	s_nop 0
	v_cndmask_b32_e32 v92, v92, v94, vcc
	v_rsq_f32_e32 v92, v92
	s_nop 0
	v_mul_f32_e32 v94, 0x45800000, v92
	v_cndmask_b32_e32 v94, v92, v94, vcc
	s_cbranch_scc1 .LBB0_605
	s_cmp_lg_u32 s10, 1
	v_mov_b32_e32 v92, 1.0
	s_cbranch_scc1 .LBB0_604
	v_mov_b32_e32 v92, v94

; __device__ __forceinline__ unsigned cvtpk(float lo, float hi) { f32x2 v = {lo, hi}; bf16x2_t b = __builtin_convertvector(v, bf16x2_t); return __builtin_bit_cast(unsigned, b); }
; #define EPI_LOOP_ROWS for (int ai = 0; ai < 2; ++ai) _Pragma("unroll") for (int m = 0; m < 4; ++m)
;     __device__ __forceinline__ void operator()(const f32x4 (&acc)[2][2][4][2], const Unit& u, int wv) const {
;     ...
;         EPI_LOOP_ROWS { const f32x4* p_ = (const f32x4*)(RSM + (size_t)(row0 + ai * HALF + m * 16) * 8); const f32x4 a_ = p_[0], b_ = p_[1];
;             rq[ai][m] = rsqrtf(((a_.x + a_.y) + (a_.z + a_.w)) * (1.0f / 256.0f) + EPS); rkv[ai][m] = rsqrtf(((b_.x + b_.y) + (b_.z + b_.w)) * (1.0f / 128.0f) + EPS); }
; #pragma unroll
;         for (int bj = 0; bj < 2; ++bj) {
;             const int cg = u.pn * BM + bj * HALF + wc * 32;
;             const bool rope = (cg < 768) && ((cg % 96) == 64);
;             const int kind = (cg < 384) ? 0 : ((cg < 768 && rope) ? 2 : 1);
; #pragma unroll
;             EPI_LOOP_ROWS { const int row = row0 + ai * HALF + m * 16; f32x4 v0 = acc[ai][bj][m][0], v1 = acc[ai][bj][m][1];
;                 const float sc = kind == 0 ? qscale * rq[ai][m] : (kind == 1 ? rkv[ai][m] : 1.0f);
;                 if (rope) { const int pos = row & (SEQ - 1); const f32x4 c = *(const f32x4*)(rcos + pos * 16 + 4 * fq), s = *(const f32x4*)(rsin + pos * 16 + 4 * fq);
;                     const f32x4 a = v0 * c - v1 * s, b = v0 * s + v1 * c; v0 = a; v1 = b; }
;                 v0 = v0 * sc; v1 = v1 * sc;
;                 bf16_t* p = O + (size_t)row * 1024 + cg + 4 * fq;
;                 u32x2 w0, w1; w0.x = cvtpk(v0[0], v0[1]); w0.y = cvtpk(v0[2], v0[3]); w1.x = cvtpk(v1[0], v1[1]); w1.y = cvtpk(v1[2], v1[3]);
;                 *(u32x2*)p = w0; *(u32x2*)(p + 16) = w1; } }
.LBB0_609:
	s_nop 0
	v_pk_mul_f32 v[96:97], v[92:93], v[82:83] op_sel_hi:[0,1]
	v_lshlrev_b64 v[82:83], 11, v[212:213]
	v_lshl_add_u64 v[82:83], s[12:13], 0, v[82:83]
	v_pk_mul_f32 v[88:89], v[92:93], v[88:89] op_sel_hi:[0,1]
	v_pk_mul_f32 v[86:87], v[92:93], v[86:87] op_sel_hi:[0,1]
	v_lshl_add_u64 v[82:83], s[78:79], 1, v[82:83]
	v_pk_mul_f32 v[84:85], v[92:93], v[84:85] op_sel_hi:[0,1]
	v_lshl_add_u64 v[82:83], v[82:83], 0, v[0:1]
	v_cvt_pk_bf16_f32 v86, v86, v87
	v_cvt_pk_bf16_f32 v87, v88, v89
	v_cvt_pk_bf16_f32 v88, v96, v97
	v_cvt_pk_bf16_f32 v89, v84, v85
	v_mov_b32_e32 v238, v86
	v_mov_b32_e32 v239, v87
	v_mov_b32_e32 v240, v88
	v_mov_b32_e32 v241, v89
	s_nop 1
	v_permlane16_swap_b32 v238, v240
	v_permlane16_swap_b32 v239, v241
	v_lshl_add_u64 v[242:243], v[82:83], 0, v[244:245]
	global_store_dwordx4 v[242:243], v[238:241], off
	s_nop 1
	v_mov_b32_e32 v84, v135
	v_mov_b32_e32 v85, v136
	v_mov_b32_e32 v135, v137
	v_mov_b32_e32 v86, v131
	v_mov_b32_e32 v87, v132
	v_mov_b32_e32 v131, v133
	v_pk_add_f32 v[84:85], v[84:85], v[134:135]
	v_pk_add_f32 v[86:87], v[86:87], v[130:131]
	v_mov_b32_e32 v89, v84
	v_mov_b32_e32 v88, v86
	v_mov_b32_e32 v84, v87
	v_pk_add_f32 v[84:85], v[88:89], v[84:85]
	s_cmp_lt_i32 s10, 1
	v_pk_fma_f32 v[84:85], v[84:85], s[0:1], v[194:195] op_sel_hi:[1,1,0]
	s_mov_b64 s[80:81], -1
	v_mul_f32_e32 v86, 0x4b800000, v84
	v_cmp_gt_f32_e32 vcc, s97, v84
	v_cmp_gt_f32_e64 s[6:7], s97, v85
	s_nop 0
	v_cndmask_b32_e32 v84, v84, v86, vcc
	v_rsq_f32_e32 v84, v84
	s_nop 0
	v_mul_f32_e32 v86, 0x45800000, v84
	v_cndmask_b32_e32 v86, v84, v86, vcc
	s_cbranch_scc1 .LBB0_613
	s_cmp_lg_u32 s10, 1
	v_mov_b32_e32 v84, 1.0
	s_cbranch_scc1 .LBB0_612
	v_mov_b32_e32 v84, v86

; __device__ __forceinline__ unsigned cvtpk(float lo, float hi) { f32x2 v = {lo, hi}; bf16x2_t b = __builtin_convertvector(v, bf16x2_t); return __builtin_bit_cast(unsigned, b); }
; #define EPI_LOOP_ROWS for (int ai = 0; ai < 2; ++ai) _Pragma("unroll") for (int m = 0; m < 4; ++m)
;     __device__ __forceinline__ void operator()(const f32x4 (&acc)[2][2][4][2], const Unit& u, int wv) const {
;     ...
;         EPI_LOOP_ROWS { const f32x4* p_ = (const f32x4*)(RSM + (size_t)(row0 + ai * HALF + m * 16) * 8); const f32x4 a_ = p_[0], b_ = p_[1];
;             rq[ai][m] = rsqrtf(((a_.x + a_.y) + (a_.z + a_.w)) * (1.0f / 256.0f) + EPS); rkv[ai][m] = rsqrtf(((b_.x + b_.y) + (b_.z + b_.w)) * (1.0f / 128.0f) + EPS); }
; #pragma unroll
;         for (int bj = 0; bj < 2; ++bj) {
;             const int cg = u.pn * BM + bj * HALF + wc * 32;
;             const bool rope = (cg < 768) && ((cg % 96) == 64);
;             const int kind = (cg < 384) ? 0 : ((cg < 768 && rope) ? 2 : 1);
; #pragma unroll
;             EPI_LOOP_ROWS { const int row = row0 + ai * HALF + m * 16; f32x4 v0 = acc[ai][bj][m][0], v1 = acc[ai][bj][m][1];
;                 const float sc = kind == 0 ? qscale * rq[ai][m] : (kind == 1 ? rkv[ai][m] : 1.0f);
;                 if (rope) { const int pos = row & (SEQ - 1); const f32x4 c = *(const f32x4*)(rcos + pos * 16 + 4 * fq), s = *(const f32x4*)(rsin + pos * 16 + 4 * fq);
;                     const f32x4 a = v0 * c - v1 * s, b = v0 * s + v1 * c; v0 = a; v1 = b; }
;                 v0 = v0 * sc; v1 = v1 * sc;
;                 bf16_t* p = O + (size_t)row * 1024 + cg + 4 * fq;
;                 u32x2 w0, w1; w0.x = cvtpk(v0[0], v0[1]); w0.y = cvtpk(v0[2], v0[3]); w1.x = cvtpk(v1[0], v1[1]); w1.y = cvtpk(v1[2], v1[3]);
;                 *(u32x2*)p = w0; *(u32x2*)(p + 16) = w1; } }
.LBB0_617:
	s_nop 0
	v_pk_mul_f32 v[88:89], v[84:85], v[74:75] op_sel_hi:[0,1]
	v_lshlrev_b64 v[74:75], 11, v[210:211]
	v_lshl_add_u64 v[74:75], s[12:13], 0, v[74:75]
	v_pk_mul_f32 v[80:81], v[84:85], v[80:81] op_sel_hi:[0,1]
	v_pk_mul_f32 v[78:79], v[84:85], v[78:79] op_sel_hi:[0,1]
	v_lshl_add_u64 v[74:75], s[78:79], 1, v[74:75]
	v_pk_mul_f32 v[76:77], v[84:85], v[76:77] op_sel_hi:[0,1]
	v_lshl_add_u64 v[74:75], v[74:75], 0, v[0:1]
	v_cvt_pk_bf16_f32 v78, v78, v79
	v_cvt_pk_bf16_f32 v79, v80, v81
	v_cvt_pk_bf16_f32 v80, v88, v89
	v_cvt_pk_bf16_f32 v81, v76, v77
	v_mov_b32_e32 v238, v78
	v_mov_b32_e32 v239, v79
	v_mov_b32_e32 v240, v80
	v_mov_b32_e32 v241, v81
	s_nop 1
	v_permlane16_swap_b32 v238, v240
	v_permlane16_swap_b32 v239, v241
	v_lshl_add_u64 v[242:243], v[74:75], 0, v[244:245]
	global_store_dwordx4 v[242:243], v[238:241], off
	s_nop 1
	v_mov_b32_e32 v76, v119
	v_mov_b32_e32 v77, v120
	v_mov_b32_e32 v119, v121
	v_mov_b32_e32 v78, v115
	v_mov_b32_e32 v79, v116
	v_mov_b32_e32 v115, v117
	v_pk_add_f32 v[76:77], v[76:77], v[118:119]
	v_pk_add_f32 v[78:79], v[78:79], v[114:115]
	v_mov_b32_e32 v81, v76
	v_mov_b32_e32 v80, v78
	v_mov_b32_e32 v76, v79
	v_pk_add_f32 v[76:77], v[80:81], v[76:77]
	s_cmp_lt_i32 s10, 1
	v_pk_fma_f32 v[76:77], v[76:77], s[0:1], v[194:195] op_sel_hi:[1,1,0]
	s_mov_b64 s[80:81], -1
	v_mul_f32_e32 v78, 0x4b800000, v76
	v_cmp_gt_f32_e32 vcc, s97, v76
	v_cmp_gt_f32_e64 s[6:7], s97, v77
	s_nop 0
	v_cndmask_b32_e32 v76, v76, v78, vcc
	v_rsq_f32_e32 v76, v76
	s_nop 0
	v_mul_f32_e32 v78, 0x45800000, v76
	v_cndmask_b32_e32 v78, v76, v78, vcc
	s_cbranch_scc1 .LBB0_621
	s_cmp_lg_u32 s10, 1
	v_mov_b32_e32 v76, 1.0
	s_cbranch_scc1 .LBB0_620
	v_mov_b32_e32 v76, v78

; __device__ __forceinline__ unsigned cvtpk(float lo, float hi) { f32x2 v = {lo, hi}; bf16x2_t b = __builtin_convertvector(v, bf16x2_t); return __builtin_bit_cast(unsigned, b); }
; #define EPI_LOOP_ROWS for (int ai = 0; ai < 2; ++ai) _Pragma("unroll") for (int m = 0; m < 4; ++m)
;     __device__ __forceinline__ void operator()(const f32x4 (&acc)[2][2][4][2], const Unit& u, int wv) const {
;     ...
;         for (int bj = 0; bj < 2; ++bj) {
;             const int cg = u.pn * BM + bj * HALF + wc * 32;
;             const bool rope = (cg < 768) && ((cg % 96) == 64);
;             const int kind = (cg < 384) ? 0 : ((cg < 768 && rope) ? 2 : 1);
; #pragma unroll
;             EPI_LOOP_ROWS { const int row = row0 + ai * HALF + m * 16; f32x4 v0 = acc[ai][bj][m][0], v1 = acc[ai][bj][m][1];
;                 const float sc = kind == 0 ? qscale * rq[ai][m] : (kind == 1 ? rkv[ai][m] : 1.0f);
;                 if (rope) { const int pos = row & (SEQ - 1); const f32x4 c = *(const f32x4*)(rcos + pos * 16 + 4 * fq), s = *(const f32x4*)(rsin + pos * 16 + 4 * fq);
;                     const f32x4 a = v0 * c - v1 * s, b = v0 * s + v1 * c; v0 = a; v1 = b; }
;                 v0 = v0 * sc; v1 = v1 * sc;
;                 bf16_t* p = O + (size_t)row * 1024 + cg + 4 * fq;
;                 u32x2 w0, w1; w0.x = cvtpk(v0[0], v0[1]); w0.y = cvtpk(v0[2], v0[3]); w1.x = cvtpk(v1[0], v1[1]); w1.y = cvtpk(v1[2], v1[3]);
;                 *(u32x2*)p = w0; *(u32x2*)(p + 16) = w1; } }
.LBB0_625:
	s_nop 0
	v_pk_mul_f32 v[80:81], v[76:77], v[66:67] op_sel_hi:[0,1]
	v_lshlrev_b64 v[66:67], 11, v[208:209]
	v_lshl_add_u64 v[66:67], s[12:13], 0, v[66:67]
	s_or_b32 s0, s78, 0x80
	v_pk_mul_f32 v[72:73], v[76:77], v[72:73] op_sel_hi:[0,1]
	v_pk_mul_f32 v[70:71], v[76:77], v[70:71] op_sel_hi:[0,1]
	v_lshl_add_u64 v[66:67], s[78:79], 1, v[66:67]
	s_cmpk_lt_i32 s0, 0x300
	v_pk_mul_f32 v[68:69], v[76:77], v[68:69] op_sel_hi:[0,1]
	v_lshl_add_u64 v[66:67], v[66:67], 0, v[0:1]
	v_cvt_pk_bf16_f32 v70, v70, v71
	v_cvt_pk_bf16_f32 v71, v72, v73
	s_cselect_b64 s[4:5], -1, 0
	s_cmpk_gt_i32 s0, 0x2ff
	s_mov_b64 s[6:7], 0
	v_cvt_pk_bf16_f32 v72, v80, v81
	v_cvt_pk_bf16_f32 v73, v68, v69
	v_mov_b32_e32 v238, v70
	v_mov_b32_e32 v239, v71
	v_mov_b32_e32 v240, v72
	v_mov_b32_e32 v241, v73
	s_nop 1
	v_permlane16_swap_b32 v238, v240
	v_permlane16_swap_b32 v239, v241
	v_lshl_add_u64 v[242:243], v[66:67], 0, v[244:245]
	global_store_dwordx4 v[242:243], v[238:241], off
	s_nop 1
	s_cbranch_scc1 .LBB0_627
	s_mul_hi_i32 s1, s0, 0x2aaaaaab
	s_lshr_b32 s6, s1, 31
	s_lshr_b32 s1, s1, 4
	s_add_i32 s1, s1, s6
	s_mulk_i32 s1, 0x60
	s_sub_i32 s1, s0, s1
	s_cmp_eq_u32 s1, 64
	s_cselect_b64 s[6:7], -1, 0

; __device__ __forceinline__ unsigned cvtpk(float lo, float hi) { f32x2 v = {lo, hi}; bf16x2_t b = __builtin_convertvector(v, bf16x2_t); return __builtin_bit_cast(unsigned, b); }
; #define EPI_LOOP_ROWS for (int ai = 0; ai < 2; ++ai) _Pragma("unroll") for (int m = 0; m < 4; ++m)
;     __device__ __forceinline__ void operator()(const f32x4 (&acc)[2][2][4][2], const Unit& u, int wv) const {
;     ...
;             EPI_LOOP_ROWS { const int row = row0 + ai * HALF + m * 16; f32x4 v0 = acc[ai][bj][m][0], v1 = acc[ai][bj][m][1];
;                 const float sc = kind == 0 ? qscale * rq[ai][m] : (kind == 1 ? rkv[ai][m] : 1.0f);
;                 if (rope) { const int pos = row & (SEQ - 1); const f32x4 c = *(const f32x4*)(rcos + pos * 16 + 4 * fq), s = *(const f32x4*)(rsin + pos * 16 + 4 * fq);
;                     const f32x4 a = v0 * c - v1 * s, b = v0 * s + v1 * c; v0 = a; v1 = b; }
;                 v0 = v0 * sc; v1 = v1 * sc;
;                 bf16_t* p = O + (size_t)row * 1024 + cg + 4 * fq;
;                 u32x2 w0, w1; w0.x = cvtpk(v0[0], v0[1]); w0.y = cvtpk(v0[2], v0[3]); w1.x = cvtpk(v1[0], v1[1]); w1.y = cvtpk(v1[2], v1[3]);
;                 *(u32x2*)p = w0; *(u32x2*)(p + 16) = w1; } }
.LBB0_631:
	v_pk_mul_f32 v[64:65], v[68:69], v[64:65] op_sel_hi:[0,1]
	v_pk_mul_f32 v[62:63], v[68:69], v[62:63] op_sel_hi:[0,1]
	v_pk_mul_f32 v[58:59], v[68:69], v[58:59] op_sel_hi:[0,1]
	v_pk_mul_f32 v[60:61], v[68:69], v[60:61] op_sel_hi:[0,1]
	v_cvt_pk_bf16_f32 v62, v62, v63
	v_cvt_pk_bf16_f32 v63, v64, v65
	v_cvt_pk_bf16_f32 v58, v58, v59
	s_cmp_lt_i32 s10, 1
	s_mov_b64 s[6:7], -1
	v_cvt_pk_bf16_f32 v59, v60, v61
	v_mov_b32_e32 v238, v62
	v_mov_b32_e32 v239, v63
	v_mov_b32_e32 v240, v58
	v_mov_b32_e32 v241, v59
	s_nop 1
	v_permlane16_swap_b32 v238, v240
	v_permlane16_swap_b32 v239, v241
	v_lshl_add_u64 v[242:243], v[138:139], 0, v[244:245]
	global_store_dwordx4 v[242:243], v[238:241], off offset:256
	s_nop 1
	s_cbranch_scc0 .LBB0_666
	s_andn2_b64 vcc, exec, s[6:7]
	s_cbranch_vccz .LBB0_669

; __device__ __forceinline__ unsigned cvtpk(float lo, float hi) { f32x2 v = {lo, hi}; bf16x2_t b = __builtin_convertvector(v, bf16x2_t); return __builtin_bit_cast(unsigned, b); }
; #define EPI_LOOP_ROWS for (int ai = 0; ai < 2; ++ai) _Pragma("unroll") for (int m = 0; m < 4; ++m)
;     __device__ __forceinline__ void operator()(const f32x4 (&acc)[2][2][4][2], const Unit& u, int wv) const {
;     ...
;             EPI_LOOP_ROWS { const int row = row0 + ai * HALF + m * 16; f32x4 v0 = acc[ai][bj][m][0], v1 = acc[ai][bj][m][1];
;                 const float sc = kind == 0 ? qscale * rq[ai][m] : (kind == 1 ? rkv[ai][m] : 1.0f);
;                 if (rope) { const int pos = row & (SEQ - 1); const f32x4 c = *(const f32x4*)(rcos + pos * 16 + 4 * fq), s = *(const f32x4*)(rsin + pos * 16 + 4 * fq);
;                     const f32x4 a = v0 * c - v1 * s, b = v0 * s + v1 * c; v0 = a; v1 = b; }
;                 v0 = v0 * sc; v1 = v1 * sc;
;                 bf16_t* p = O + (size_t)row * 1024 + cg + 4 * fq;
;                 u32x2 w0, w1; w0.x = cvtpk(v0[0], v0[1]); w0.y = cvtpk(v0[2], v0[3]); w1.x = cvtpk(v1[0], v1[1]); w1.y = cvtpk(v1[2], v1[3]);
;                 *(u32x2*)p = w0; *(u32x2*)(p + 16) = w1; } }
.LBB0_635:
	v_pk_mul_f32 v[56:57], v[58:59], v[56:57] op_sel_hi:[0,1]
	v_pk_mul_f32 v[54:55], v[58:59], v[54:55] op_sel_hi:[0,1]
	v_pk_mul_f32 v[50:51], v[58:59], v[50:51] op_sel_hi:[0,1]
	v_pk_mul_f32 v[52:53], v[58:59], v[52:53] op_sel_hi:[0,1]
	v_cvt_pk_bf16_f32 v54, v54, v55
	v_cvt_pk_bf16_f32 v55, v56, v57
	v_cvt_pk_bf16_f32 v50, v50, v51
	s_cmp_lt_i32 s10, 1
	s_mov_b64 s[6:7], -1
	v_cvt_pk_bf16_f32 v51, v52, v53
	v_mov_b32_e32 v238, v54
	v_mov_b32_e32 v239, v55
	v_mov_b32_e32 v240, v50
	v_mov_b32_e32 v241, v51
	s_nop 1
	v_permlane16_swap_b32 v238, v240
	v_permlane16_swap_b32 v239, v241
	v_lshl_add_u64 v[242:243], v[122:123], 0, v[244:245]
	global_store_dwordx4 v[242:243], v[238:241], off offset:256
	s_nop 1
	s_cbranch_scc0 .LBB0_670
	s_andn2_b64 vcc, exec, s[6:7]
	s_cbranch_vccz .LBB0_673

; __device__ __forceinline__ unsigned cvtpk(float lo, float hi) { f32x2 v = {lo, hi}; bf16x2_t b = __builtin_convertvector(v, bf16x2_t); return __builtin_bit_cast(unsigned, b); }
; #define EPI_LOOP_ROWS for (int ai = 0; ai < 2; ++ai) _Pragma("unroll") for (int m = 0; m < 4; ++m)
;     __device__ __forceinline__ void operator()(const f32x4 (&acc)[2][2][4][2], const Unit& u, int wv) const {
;     ...
;             EPI_LOOP_ROWS { const int row = row0 + ai * HALF + m * 16; f32x4 v0 = acc[ai][bj][m][0], v1 = acc[ai][bj][m][1];
;                 const float sc = kind == 0 ? qscale * rq[ai][m] : (kind == 1 ? rkv[ai][m] : 1.0f);
;                 if (rope) { const int pos = row & (SEQ - 1); const f32x4 c = *(const f32x4*)(rcos + pos * 16 + 4 * fq), s = *(const f32x4*)(rsin + pos * 16 + 4 * fq);
;                     const f32x4 a = v0 * c - v1 * s, b = v0 * s + v1 * c; v0 = a; v1 = b; }
;                 v0 = v0 * sc; v1 = v1 * sc;
;                 bf16_t* p = O + (size_t)row * 1024 + cg + 4 * fq;
;                 u32x2 w0, w1; w0.x = cvtpk(v0[0], v0[1]); w0.y = cvtpk(v0[2], v0[3]); w1.x = cvtpk(v1[0], v1[1]); w1.y = cvtpk(v1[2], v1[3]);
;                 *(u32x2*)p = w0; *(u32x2*)(p + 16) = w1; } }
.LBB0_639:
	v_pk_mul_f32 v[48:49], v[50:51], v[48:49] op_sel_hi:[0,1]
	v_pk_mul_f32 v[46:47], v[50:51], v[46:47] op_sel_hi:[0,1]
	v_pk_mul_f32 v[42:43], v[50:51], v[42:43] op_sel_hi:[0,1]
	v_pk_mul_f32 v[44:45], v[50:51], v[44:45] op_sel_hi:[0,1]
	v_cvt_pk_bf16_f32 v46, v46, v47
	v_cvt_pk_bf16_f32 v47, v48, v49
	v_cvt_pk_bf16_f32 v42, v42, v43
	s_cmp_lt_i32 s10, 1
	s_mov_b64 s[6:7], -1
	v_cvt_pk_bf16_f32 v43, v44, v45
	v_mov_b32_e32 v238, v46
	v_mov_b32_e32 v239, v47
	v_mov_b32_e32 v240, v42
	v_mov_b32_e32 v241, v43
	s_nop 1
	v_permlane16_swap_b32 v238, v240
	v_permlane16_swap_b32 v239, v241
	v_lshl_add_u64 v[242:243], v[106:107], 0, v[244:245]
	global_store_dwordx4 v[242:243], v[238:241], off offset:256
	s_nop 1
	s_cbranch_scc0 .LBB0_674
	s_andn2_b64 vcc, exec, s[6:7]
	s_cbranch_vccz .LBB0_677

; __device__ __forceinline__ unsigned cvtpk(float lo, float hi) { f32x2 v = {lo, hi}; bf16x2_t b = __builtin_convertvector(v, bf16x2_t); return __builtin_bit_cast(unsigned, b); }
; #define EPI_LOOP_ROWS for (int ai = 0; ai < 2; ++ai) _Pragma("unroll") for (int m = 0; m < 4; ++m)
;     __device__ __forceinline__ void operator()(const f32x4 (&acc)[2][2][4][2], const Unit& u, int wv) const {
;     ...
;             EPI_LOOP_ROWS { const int row = row0 + ai * HALF + m * 16; f32x4 v0 = acc[ai][bj][m][0], v1 = acc[ai][bj][m][1];
;                 const float sc = kind == 0 ? qscale * rq[ai][m] : (kind == 1 ? rkv[ai][m] : 1.0f);
;                 if (rope) { const int pos = row & (SEQ - 1); const f32x4 c = *(const f32x4*)(rcos + pos * 16 + 4 * fq), s = *(const f32x4*)(rsin + pos * 16 + 4 * fq);
;                     const f32x4 a = v0 * c - v1 * s, b = v0 * s + v1 * c; v0 = a; v1 = b; }
;                 v0 = v0 * sc; v1 = v1 * sc;
;                 bf16_t* p = O + (size_t)row * 1024 + cg + 4 * fq;
;                 u32x2 w0, w1; w0.x = cvtpk(v0[0], v0[1]); w0.y = cvtpk(v0[2], v0[3]); w1.x = cvtpk(v1[0], v1[1]); w1.y = cvtpk(v1[2], v1[3]);
;                 *(u32x2*)p = w0; *(u32x2*)(p + 16) = w1; } }
.LBB0_643:
	v_pk_mul_f32 v[40:41], v[42:43], v[40:41] op_sel_hi:[0,1]
	v_pk_mul_f32 v[38:39], v[42:43], v[38:39] op_sel_hi:[0,1]
	v_pk_mul_f32 v[34:35], v[42:43], v[34:35] op_sel_hi:[0,1]
	v_pk_mul_f32 v[36:37], v[42:43], v[36:37] op_sel_hi:[0,1]
	v_cvt_pk_bf16_f32 v38, v38, v39
	v_cvt_pk_bf16_f32 v39, v40, v41
	v_cvt_pk_bf16_f32 v34, v34, v35
	s_cmp_lt_i32 s10, 1
	s_mov_b64 s[6:7], -1
	v_cvt_pk_bf16_f32 v35, v36, v37
	v_mov_b32_e32 v238, v38
	v_mov_b32_e32 v239, v39
	v_mov_b32_e32 v240, v34
	v_mov_b32_e32 v241, v35
	s_nop 1
	v_permlane16_swap_b32 v238, v240
	v_permlane16_swap_b32 v239, v241
	v_lshl_add_u64 v[242:243], v[98:99], 0, v[244:245]
	global_store_dwordx4 v[242:243], v[238:241], off offset:256
	s_nop 1
	s_cbranch_scc0 .LBB0_678
	s_andn2_b64 vcc, exec, s[6:7]
	s_cbranch_vccz .LBB0_681

; __device__ __forceinline__ unsigned cvtpk(float lo, float hi) { f32x2 v = {lo, hi}; bf16x2_t b = __builtin_convertvector(v, bf16x2_t); return __builtin_bit_cast(unsigned, b); }
; #define EPI_LOOP_ROWS for (int ai = 0; ai < 2; ++ai) _Pragma("unroll") for (int m = 0; m < 4; ++m)
;     __device__ __forceinline__ void operator()(const f32x4 (&acc)[2][2][4][2], const Unit& u, int wv) const {
;     ...
;             EPI_LOOP_ROWS { const int row = row0 + ai * HALF + m * 16; f32x4 v0 = acc[ai][bj][m][0], v1 = acc[ai][bj][m][1];
;                 const float sc = kind == 0 ? qscale * rq[ai][m] : (kind == 1 ? rkv[ai][m] : 1.0f);
;                 if (rope) { const int pos = row & (SEQ - 1); const f32x4 c = *(const f32x4*)(rcos + pos * 16 + 4 * fq), s = *(const f32x4*)(rsin + pos * 16 + 4 * fq);
;                     const f32x4 a = v0 * c - v1 * s, b = v0 * s + v1 * c; v0 = a; v1 = b; }
;                 v0 = v0 * sc; v1 = v1 * sc;
;                 bf16_t* p = O + (size_t)row * 1024 + cg + 4 * fq;
;                 u32x2 w0, w1; w0.x = cvtpk(v0[0], v0[1]); w0.y = cvtpk(v0[2], v0[3]); w1.x = cvtpk(v1[0], v1[1]); w1.y = cvtpk(v1[2], v1[3]);
;                 *(u32x2*)p = w0; *(u32x2*)(p + 16) = w1; } }
.LBB0_647:
	v_pk_mul_f32 v[32:33], v[34:35], v[32:33] op_sel_hi:[0,1]
	v_pk_mul_f32 v[30:31], v[34:35], v[30:31] op_sel_hi:[0,1]
	v_pk_mul_f32 v[26:27], v[34:35], v[26:27] op_sel_hi:[0,1]
	v_pk_mul_f32 v[28:29], v[34:35], v[28:29] op_sel_hi:[0,1]
	v_cvt_pk_bf16_f32 v30, v30, v31
	v_cvt_pk_bf16_f32 v31, v32, v33
	v_cvt_pk_bf16_f32 v26, v26, v27
	s_cmp_lt_i32 s10, 1
	s_mov_b64 s[6:7], -1
	v_cvt_pk_bf16_f32 v27, v28, v29
	v_mov_b32_e32 v238, v30
	v_mov_b32_e32 v239, v31
	v_mov_b32_e32 v240, v26
	v_mov_b32_e32 v241, v27
	s_nop 1
	v_permlane16_swap_b32 v238, v240
	v_permlane16_swap_b32 v239, v241
	v_lshl_add_u64 v[242:243], v[90:91], 0, v[244:245]
	global_store_dwordx4 v[242:243], v[238:241], off offset:256
	s_nop 1
	s_cbranch_scc0 .LBB0_682
	s_andn2_b64 vcc, exec, s[6:7]
	s_cbranch_vccz .LBB0_685

; __device__ __forceinline__ unsigned cvtpk(float lo, float hi) { f32x2 v = {lo, hi}; bf16x2_t b = __builtin_convertvector(v, bf16x2_t); return __builtin_bit_cast(unsigned, b); }
; #define EPI_LOOP_ROWS for (int ai = 0; ai < 2; ++ai) _Pragma("unroll") for (int m = 0; m < 4; ++m)
;     __device__ __forceinline__ void operator()(const f32x4 (&acc)[2][2][4][2], const Unit& u, int wv) const {
;     ...
;             EPI_LOOP_ROWS { const int row = row0 + ai * HALF + m * 16; f32x4 v0 = acc[ai][bj][m][0], v1 = acc[ai][bj][m][1];
;                 const float sc = kind == 0 ? qscale * rq[ai][m] : (kind == 1 ? rkv[ai][m] : 1.0f);
;                 if (rope) { const int pos = row & (SEQ - 1); const f32x4 c = *(const f32x4*)(rcos + pos * 16 + 4 * fq), s = *(const f32x4*)(rsin + pos * 16 + 4 * fq);
;                     const f32x4 a = v0 * c - v1 * s, b = v0 * s + v1 * c; v0 = a; v1 = b; }
;                 v0 = v0 * sc; v1 = v1 * sc;
;                 bf16_t* p = O + (size_t)row * 1024 + cg + 4 * fq;
;                 u32x2 w0, w1; w0.x = cvtpk(v0[0], v0[1]); w0.y = cvtpk(v0[2], v0[3]); w1.x = cvtpk(v1[0], v1[1]); w1.y = cvtpk(v1[2], v1[3]);
;                 *(u32x2*)p = w0; *(u32x2*)(p + 16) = w1; } }
.LBB0_651:
	v_pk_mul_f32 v[24:25], v[26:27], v[24:25] op_sel_hi:[0,1]
	v_pk_mul_f32 v[22:23], v[26:27], v[22:23] op_sel_hi:[0,1]
	v_pk_mul_f32 v[18:19], v[26:27], v[18:19] op_sel_hi:[0,1]
	v_pk_mul_f32 v[20:21], v[26:27], v[20:21] op_sel_hi:[0,1]
	v_cvt_pk_bf16_f32 v22, v22, v23
	v_cvt_pk_bf16_f32 v23, v24, v25
	v_cvt_pk_bf16_f32 v18, v18, v19
	s_cmp_lt_i32 s10, 1
	s_mov_b64 s[6:7], -1
	v_cvt_pk_bf16_f32 v19, v20, v21
	v_mov_b32_e32 v238, v22
	v_mov_b32_e32 v239, v23
	v_mov_b32_e32 v240, v18
	v_mov_b32_e32 v241, v19
	s_nop 1
	v_permlane16_swap_b32 v238, v240
	v_permlane16_swap_b32 v239, v241
	v_lshl_add_u64 v[242:243], v[82:83], 0, v[244:245]
	global_store_dwordx4 v[242:243], v[238:241], off offset:256
	s_nop 1
	s_cbranch_scc0 .LBB0_686
	s_andn2_b64 vcc, exec, s[6:7]
	s_cbranch_vccz .LBB0_689

; __device__ __forceinline__ unsigned cvtpk(float lo, float hi) { f32x2 v = {lo, hi}; bf16x2_t b = __builtin_convertvector(v, bf16x2_t); return __builtin_bit_cast(unsigned, b); }
; #define EPI_LOOP_ROWS for (int ai = 0; ai < 2; ++ai) _Pragma("unroll") for (int m = 0; m < 4; ++m)
;     __device__ __forceinline__ void operator()(const f32x4 (&acc)[2][2][4][2], const Unit& u, int wv) const {
;     ...
;             EPI_LOOP_ROWS { const int row = row0 + ai * HALF + m * 16; f32x4 v0 = acc[ai][bj][m][0], v1 = acc[ai][bj][m][1];
;                 const float sc = kind == 0 ? qscale * rq[ai][m] : (kind == 1 ? rkv[ai][m] : 1.0f);
;                 if (rope) { const int pos = row & (SEQ - 1); const f32x4 c = *(const f32x4*)(rcos + pos * 16 + 4 * fq), s = *(const f32x4*)(rsin + pos * 16 + 4 * fq);
;                     const f32x4 a = v0 * c - v1 * s, b = v0 * s + v1 * c; v0 = a; v1 = b; }
;                 v0 = v0 * sc; v1 = v1 * sc;
;                 bf16_t* p = O + (size_t)row * 1024 + cg + 4 * fq;
;                 u32x2 w0, w1; w0.x = cvtpk(v0[0], v0[1]); w0.y = cvtpk(v0[2], v0[3]); w1.x = cvtpk(v1[0], v1[1]); w1.y = cvtpk(v1[2], v1[3]);
;                 *(u32x2*)p = w0; *(u32x2*)(p + 16) = w1; } }
.LBB0_655:
	v_pk_mul_f32 v[16:17], v[18:19], v[16:17] op_sel_hi:[0,1]
	v_pk_mul_f32 v[14:15], v[18:19], v[14:15] op_sel_hi:[0,1]
	v_pk_mul_f32 v[10:11], v[18:19], v[10:11] op_sel_hi:[0,1]
	v_pk_mul_f32 v[12:13], v[18:19], v[12:13] op_sel_hi:[0,1]
	v_cvt_pk_bf16_f32 v14, v14, v15
	v_cvt_pk_bf16_f32 v15, v16, v17
	v_cvt_pk_bf16_f32 v10, v10, v11
	s_cmp_lt_i32 s10, 1
	s_mov_b64 s[6:7], -1
	v_cvt_pk_bf16_f32 v11, v12, v13
	v_mov_b32_e32 v238, v14
	v_mov_b32_e32 v239, v15
	v_mov_b32_e32 v240, v10
	v_mov_b32_e32 v241, v11
	s_nop 1
	v_permlane16_swap_b32 v238, v240
	v_permlane16_swap_b32 v239, v241
	v_lshl_add_u64 v[242:243], v[74:75], 0, v[244:245]
	global_store_dwordx4 v[242:243], v[238:241], off offset:256
	s_nop 1
	s_cbranch_scc0 .LBB0_690
	s_andn2_b64 vcc, exec, s[6:7]
	s_cbranch_vccz .LBB0_693

; __device__ __forceinline__ unsigned cvtpk(float lo, float hi) { f32x2 v = {lo, hi}; bf16x2_t b = __builtin_convertvector(v, bf16x2_t); return __builtin_bit_cast(unsigned, b); }
; #define EPI_LOOP_ROWS for (int ai = 0; ai < 2; ++ai) _Pragma("unroll") for (int m = 0; m < 4; ++m)
;     __device__ __forceinline__ void operator()(const f32x4 (&acc)[2][2][4][2], const Unit& u, int wv) const {
;     ...
;             EPI_LOOP_ROWS { const int row = row0 + ai * HALF + m * 16; f32x4 v0 = acc[ai][bj][m][0], v1 = acc[ai][bj][m][1];
;                 const float sc = kind == 0 ? qscale * rq[ai][m] : (kind == 1 ? rkv[ai][m] : 1.0f);
;                 if (rope) { const int pos = row & (SEQ - 1); const f32x4 c = *(const f32x4*)(rcos + pos * 16 + 4 * fq), s = *(const f32x4*)(rsin + pos * 16 + 4 * fq);
;                     const f32x4 a = v0 * c - v1 * s, b = v0 * s + v1 * c; v0 = a; v1 = b; }
;                 v0 = v0 * sc; v1 = v1 * sc;
;                 bf16_t* p = O + (size_t)row * 1024 + cg + 4 * fq;
;                 u32x2 w0, w1; w0.x = cvtpk(v0[0], v0[1]); w0.y = cvtpk(v0[2], v0[3]); w1.x = cvtpk(v1[0], v1[1]); w1.y = cvtpk(v1[2], v1[3]);
;                 *(u32x2*)p = w0; *(u32x2*)(p + 16) = w1; } }
.LBB0_659:
	v_pk_mul_f32 v[8:9], v[10:11], v[8:9] op_sel_hi:[0,1]
	v_pk_mul_f32 v[6:7], v[10:11], v[6:7] op_sel_hi:[0,1]
	v_pk_mul_f32 v[4:5], v[10:11], v[4:5] op_sel_hi:[0,1]
	v_pk_mul_f32 v[2:3], v[10:11], v[2:3] op_sel_hi:[0,1]
	v_cvt_pk_bf16_f32 v6, v6, v7
	v_cvt_pk_bf16_f32 v7, v8, v9
	s_andn2_b64 vcc, exec, s[2:3]
	s_mov_b64 s[2:3], -1
	v_cvt_pk_bf16_f32 v2, v2, v3
	v_cvt_pk_bf16_f32 v3, v4, v5
	v_mov_b32_e32 v238, v6
	v_mov_b32_e32 v239, v7
	v_mov_b32_e32 v240, v2
	v_mov_b32_e32 v241, v3
	s_nop 1
	v_permlane16_swap_b32 v238, v240
	v_permlane16_swap_b32 v239, v241
	v_lshl_add_u64 v[242:243], v[66:67], 0, v[244:245]
	global_store_dwordx4 v[242:243], v[238:241], off offset:256
	s_nop 1
	s_cbranch_vccnz .LBB0_548
	s_andn2_b64 vcc, exec, s[8:9]
	s_cbranch_vccnz .LBB0_547
	s_barrier
	s_branch .LBB0_547
